# v16 + layer-0 context rows of the post-mixer norm: the split-K slab segments are loaded three ahead (sliding window) instead of one load-wait per segment
# baseline (speedup 1.0000x reference)
; __device__ __forceinline__ f32x4 bf4(const u32x2 w) { return (f32x4){__uint_as_float(w[0] << 16), __uint_as_float(w[0] & 0xffff0000u), __uint_as_float(w[1] << 16), __uint_as_float(w[1] & 0xffff0000u)}; }
; __device__ __forceinline__ void phase_postmix(const Params& p, const Ctx& c, int l, bool last) {
;     ...
;     if (t < CTXL) { const u32x2* sl = (const u32x2*)(p.ws + OFF_Z2) + ((size_t)b * CTXL + t) * (DM / 4);
; #pragma unroll
;       for (int i = 0; i < 8; ++i) { m[i] = (f32x4){0.f, 0.f, 0.f, 0.f}; x[i] = xs[c.lane + 64 * i]; }
;       for (int s = 0; s < 8; ++s) {
; #pragma unroll
;         for (int i = 0; i < 8; ++i) m[i] += bf4(sl[(size_t)s * NB * CTXL * (DM / 4) + c.lane + 64 * i]); } }
.LBB0_1059:
	v_lshl_add_u64 v[68:69], v[66:67], 0, s[60:61]
	v_add_co_u32_e32 v70, vcc, s74, v68
	s_add_u32 s60, s60, 0x800000
	s_nop 0
	v_addc_co_u32_e32 v71, vcc, 0, v69, vcc
	global_load_dwordx2 v[206:207], v[70:71], off
	global_load_dwordx2 v[208:209], v[70:71], off offset:512
	global_load_dwordx2 v[210:211], v[70:71], off offset:1024
	s_waitcnt vmcnt(2)
	v_mov_b64_e32 v[72:73], v[206:207]
	global_load_dwordx2 v[206:207], v[70:71], off offset:1536
	s_waitcnt vmcnt(2)
	v_mov_b64_e32 v[76:77], v[208:209]
	global_load_dwordx2 v[208:209], v[70:71], off offset:2048
	v_add_co_u32_e32 v68, vcc, s75, v68
	s_addc_u32 s61, s61, 0
	s_nop 0
	v_addc_co_u32_e32 v69, vcc, 0, v69, vcc
	s_cmp_eq_u32 s60, 0x2000000
	v_lshlrev_b32_e32 v74, 16, v72
	v_and_b32_e32 v75, 0xffff0000, v72
	v_pk_add_f32 v[74:75], v[160:161], v[74:75]
	v_lshlrev_b32_e32 v160, 16, v76
	v_and_b32_e32 v161, 0xffff0000, v76
	v_pk_add_f32 v[164:165], v[164:165], v[160:161]
	s_waitcnt vmcnt(2)
	v_mov_b64_e32 v[160:161], v[210:211]
	global_load_dwordx2 v[210:211], v[70:71], off offset:2560
	v_lshlrev_b32_e32 v72, 16, v73
	v_and_b32_e32 v73, 0xffff0000, v73
	v_pk_add_f32 v[72:73], v[162:163], v[72:73]
	v_lshlrev_b32_e32 v76, 16, v77
	v_and_b32_e32 v77, 0xffff0000, v77
	v_pk_add_f32 v[76:77], v[166:167], v[76:77]
	v_lshlrev_b32_e32 v162, 16, v160
	v_and_b32_e32 v163, 0xffff0000, v160
	v_lshlrev_b32_e32 v160, 16, v161
	v_and_b32_e32 v161, 0xffff0000, v161
	v_pk_add_f32 v[170:171], v[170:171], v[160:161]
	s_waitcnt vmcnt(2)
	v_mov_b64_e32 v[160:161], v[206:207]
	global_load_dwordx2 v[206:207], v[70:71], off offset:3072
	v_pk_add_f32 v[168:169], v[168:169], v[162:163]
	v_lshlrev_b32_e32 v162, 16, v160
	v_and_b32_e32 v163, 0xffff0000, v160
	v_lshlrev_b32_e32 v160, 16, v161
	v_and_b32_e32 v161, 0xffff0000, v161
	v_pk_add_f32 v[186:187], v[186:187], v[160:161]
	s_waitcnt vmcnt(2)
	v_mov_b64_e32 v[160:161], v[208:209]
	global_load_dwordx2 v[208:209], v[70:71], off offset:3584
	v_pk_add_f32 v[182:183], v[182:183], v[162:163]
	v_lshlrev_b32_e32 v162, 16, v160
	v_and_b32_e32 v163, 0xffff0000, v160
	v_lshlrev_b32_e32 v160, 16, v161
	v_and_b32_e32 v161, 0xffff0000, v161
	v_pk_add_f32 v[178:179], v[178:179], v[160:161]
	s_waitcnt vmcnt(2)
	v_mov_b64_e32 v[160:161], v[210:211]
	global_load_dwordx2 v[210:211], v[68:69], off
	v_pk_add_f32 v[176:177], v[176:177], v[162:163]
	v_lshlrev_b32_e32 v162, 16, v160
	v_and_b32_e32 v163, 0xffff0000, v160
	v_lshlrev_b32_e32 v160, 16, v161
	v_and_b32_e32 v161, 0xffff0000, v161
	v_pk_add_f32 v[184:185], v[184:185], v[160:161]
	s_waitcnt vmcnt(2)
	v_mov_b64_e32 v[160:161], v[206:207]
	global_load_dwordx2 v[206:207], v[68:69], off offset:512
	v_pk_add_f32 v[180:181], v[180:181], v[162:163]
	s_waitcnt vmcnt(2)
	v_mov_b64_e32 v[70:71], v[208:209]
	global_load_dwordx2 v[208:209], v[68:69], off offset:1024
	v_lshlrev_b32_e32 v162, 16, v160
	v_and_b32_e32 v163, 0xffff0000, v160
	v_lshlrev_b32_e32 v160, 16, v161
	v_and_b32_e32 v161, 0xffff0000, v161
	v_pk_add_f32 v[190:191], v[190:191], v[160:161]
	v_lshlrev_b32_e32 v160, 16, v70
	v_and_b32_e32 v161, 0xffff0000, v70
	v_pk_add_f32 v[172:173], v[172:173], v[160:161]
	s_waitcnt vmcnt(2)
	v_mov_b64_e32 v[160:161], v[210:211]
	global_load_dwordx2 v[210:211], v[68:69], off offset:1536
	v_pk_add_f32 v[188:189], v[188:189], v[162:163]
	v_lshlrev_b32_e32 v70, 16, v71
	v_and_b32_e32 v71, 0xffff0000, v71
	v_pk_add_f32 v[70:71], v[174:175], v[70:71]
	v_lshlrev_b32_e32 v166, 16, v160
	v_and_b32_e32 v167, 0xffff0000, v160
	v_lshlrev_b32_e32 v160, 16, v161
	v_and_b32_e32 v161, 0xffff0000, v161
	v_pk_add_f32 v[162:163], v[72:73], v[160:161]
	s_waitcnt vmcnt(2)
	v_mov_b64_e32 v[72:73], v[206:207]
	global_load_dwordx2 v[206:207], v[68:69], off offset:2048
	v_pk_add_f32 v[160:161], v[74:75], v[166:167]
	v_lshlrev_b32_e32 v74, 16, v72
	v_and_b32_e32 v75, 0xffff0000, v72
	v_lshlrev_b32_e32 v72, 16, v73
	v_and_b32_e32 v73, 0xffff0000, v73
	v_pk_add_f32 v[166:167], v[76:77], v[72:73]
	s_waitcnt vmcnt(2)
	v_mov_b64_e32 v[72:73], v[208:209]
	global_load_dwordx2 v[208:209], v[68:69], off offset:2560
	v_pk_add_f32 v[164:165], v[164:165], v[74:75]
	v_lshlrev_b32_e32 v74, 16, v72
	v_and_b32_e32 v75, 0xffff0000, v72
	v_lshlrev_b32_e32 v72, 16, v73
	v_and_b32_e32 v73, 0xffff0000, v73
	v_pk_add_f32 v[170:171], v[170:171], v[72:73]
	s_waitcnt vmcnt(2)
	v_mov_b64_e32 v[72:73], v[210:211]
	global_load_dwordx2 v[210:211], v[68:69], off offset:3072
	v_pk_add_f32 v[168:169], v[168:169], v[74:75]
	v_lshlrev_b32_e32 v74, 16, v72
	v_and_b32_e32 v75, 0xffff0000, v72
	v_lshlrev_b32_e32 v72, 16, v73
	v_and_b32_e32 v73, 0xffff0000, v73
	v_pk_add_f32 v[186:187], v[186:187], v[72:73]
	s_waitcnt vmcnt(2)
	v_mov_b64_e32 v[72:73], v[206:207]
	global_load_dwordx2 v[206:207], v[68:69], off offset:3584
	v_pk_add_f32 v[182:183], v[182:183], v[74:75]
	v_lshlrev_b32_e32 v74, 16, v72
	v_and_b32_e32 v75, 0xffff0000, v72
	v_lshlrev_b32_e32 v72, 16, v73
	v_and_b32_e32 v73, 0xffff0000, v73
	v_pk_add_f32 v[178:179], v[178:179], v[72:73]
	s_waitcnt vmcnt(2)
	v_mov_b64_e32 v[72:73], v[208:209]
	v_pk_add_f32 v[176:177], v[176:177], v[74:75]
	v_lshlrev_b32_e32 v74, 16, v72
	v_and_b32_e32 v75, 0xffff0000, v72
	v_lshlrev_b32_e32 v72, 16, v73
	v_and_b32_e32 v73, 0xffff0000, v73
	v_pk_add_f32 v[184:185], v[184:185], v[72:73]
	s_waitcnt vmcnt(1)
	v_mov_b64_e32 v[72:73], v[210:211]
	v_pk_add_f32 v[180:181], v[180:181], v[74:75]
	s_waitcnt vmcnt(0)
	v_mov_b64_e32 v[68:69], v[206:207]
	v_lshlrev_b32_e32 v74, 16, v72
	v_and_b32_e32 v75, 0xffff0000, v72
	v_lshlrev_b32_e32 v72, 16, v73
	v_and_b32_e32 v73, 0xffff0000, v73
	v_pk_add_f32 v[190:191], v[190:191], v[72:73]
	v_lshlrev_b32_e32 v72, 16, v68
	v_and_b32_e32 v73, 0xffff0000, v68
	v_lshlrev_b32_e32 v68, 16, v69
	v_and_b32_e32 v69, 0xffff0000, v69
	v_pk_add_f32 v[188:189], v[188:189], v[74:75]
	v_pk_add_f32 v[174:175], v[70:71], v[68:69]
	v_pk_add_f32 v[172:173], v[172:173], v[72:73]
	s_cbranch_scc0 .LBB0_1059
